# P3b static unit assignment rebalanced: 3 q tiles | 2 q + 1 kv | 4 kv per workgroup instead of the XCD-chunked order (max load 3q+1kv)
# baseline (speedup 1.0000x reference)
;     __host__ __device__ bool next(int i, Unit& u) const {
;         const long L = (long)i * G + c; if (L >= nwg) return false;
;         int wgid = (int)L; { const int q = nwg / NXCD, r = nwg % NXCD, xcd = wgid % NXCD, off = wgid / NXCD; wgid = (xcd < r ? xcd * (q + 1) : r * (q + 1) + (xcd - r) * q) + off; }
;         const int nig = WGM * nN, gid = wgid / nig, fm = gid * WGM, gsz = (nM - fm) < WGM ? (nM - fm) : WGM;
;         u.pm = fm + ((wgid % nig) % gsz); u.pn = (wgid % nig) / gsz; u.kh = -1; return true;
; template <class Epi, class Sched>
; __device__ __forceinline__ void gemm_phase(PG8_LAS unsigned char* lds, const Gemm g, const Sched& S, const Epi& E) {
;     ...
;     if (!S.next(0, cur)) return;
.LBB0_644:
	s_or_b64 exec, exec, s[2:3]
	s_mov_b32 s6, s63
	s_waitcnt lgkmcnt(0)
	s_barrier
	v_mov_b32_e32 v1, v253
	s_cmpk_lt_i32 s6, 0x360
	s_cselect_b64 s[2:3], -1, 0
	s_cmpk_gt_i32 s6, 0x35f
	v_readfirstlane_b32 s97, v1
	s_cbranch_scc1 .LBB0_646
	s_cmp_lt_u32 s6, 0x70
	s_cbranch_scc0 .Lup0_b
	s_mov_b32 s54, s6
	s_mov_b32 s60, 0
	s_branch .LBB0_646
.Lup0_b:
	s_cmp_lt_u32 s6, 0xa0
	s_cbranch_scc0 .Lup0_c
	s_sub_i32 s5, s6, 0x70
	s_lshl_b32 s5, s5, 1
	s_addk_i32 s5, 0x150
	s_mul_hi_u32 s7, s5, 0xaaaaaaab
	s_lshr_b32 s54, s7, 1
	s_mul_i32 s7, s54, 3
	s_sub_i32 s60, s5, s7
	s_branch .LBB0_646
.Lup0_c:
	s_sub_i32 s5, s6, 0xa0
	s_lshl_b32 s5, s5, 2
	s_addk_i32 s5, 0x30
	s_mul_hi_u32 s7, s5, 0xaaaaaaab
	s_lshr_b32 s54, s7, 1
	s_mul_i32 s7, s54, 3
	s_sub_i32 s60, s5, s7
	s_add_i32 s60, s60, 3

;     __device__ __forceinline__ void krange(const Unit& u, int nt, int& k0, int& kn) const { if (u.kh >= 0) { kn = nt >> 1; k0 = u.kh * kn; } else { k0 = 0; kn = nt; } }
;     __device__ __forceinline__ void krange(const Unit& u, int nt, int& k0, int& kn) const { if (u.pn < 3) { k0 = 0; kn = 4; } else { k0 = 4; kn = 2; } }
;     __host__ __device__ bool next(int i, Unit& u) const {
;         const long L = (long)i * G + c; if (L >= nwg) return false;
;         int wgid = (int)L; { const int q = nwg / NXCD, r = nwg % NXCD, xcd = wgid % NXCD, off = wgid / NXCD; wgid = (xcd < r ? xcd * (q + 1) : r * (q + 1) + (xcd - r) * q) + off; }
;         const int nig = WGM * nN, gid = wgid / nig, fm = gid * WGM, gsz = (nM - fm) < WGM ? (nM - fm) : WGM;
;         u.pm = fm + ((wgid % nig) % gsz); u.pn = (wgid % nig) / gsz; u.kh = -1; return true;
; template <class Epi, class Sched>
; __device__ __forceinline__ void gemm_phase(PG8_LAS unsigned char* lds, const Gemm g, const Sched& S, const Epi& E) {
;     ...
;         const bool has_next = S.next(ui + 1, nxt);
;         int ncnt = nt; size_t nk = 0;
;         if constexpr (Sched::SPLIT) { if (has_next) { int k0_, kn_; S.krange(nxt, nt, k0_, kn_); ncnt = kn_; nk = (size_t)k0_ * kstep; } }
.LBB0_651:
	s_add_i32 s77, s77, 1
	s_mul_i32 s18, s77, s33
	s_mul_hi_u32 s19, s77, s58
	s_add_i32 s19, s19, s18
	s_mul_i32 s18, s77, s58
	s_mov_b32 s20, 0x360
	s_mov_b32 s21, 0
	s_cmp_lt_u32 s77, 3
	s_cbranch_scc1 .Lup_valid
	s_cmp_lg_u32 s77, 3
	s_cbranch_scc1 .Lup_inval
	s_cmp_lt_u32 s6, 0xa0
	s_cbranch_scc1 .Lup_inval
.Lup_valid:
	s_mov_b32 s20, 0
.Lup_inval:
	v_mov_b64_e32 v[2:3], 0x360
	v_cmp_lt_i64_e64 s[40:41], s[20:21], v[2:3]
	v_mov_b64_e32 v[2:3], 0x35f
	v_cmp_gt_i64_e64 s[38:39], s[20:21], v[2:3]
	s_and_b64 vcc, exec, s[38:39]
	s_cbranch_vccnz .LBB0_653
	s_cmp_lt_u32 s6, 0x70
	s_cbranch_scc0 .Lup_b
	s_mov_b32 s62, s6
	s_mov_b32 s7, s77
	s_branch .LBB0_653
.Lup_b:
	s_cmp_lt_u32 s6, 0xa0
	s_cbranch_scc0 .Lup_c
	s_sub_i32 s18, s6, 0x70
	s_cmp_lt_u32 s77, 2
	s_cbranch_scc0 .Lup_b2
	s_lshl_b32 s18, s18, 1
	s_add_i32 s18, s18, s77
	s_addk_i32 s18, 0x150
	s_mul_hi_u32 s19, s18, 0xaaaaaaab
	s_lshr_b32 s62, s19, 1
	s_mul_i32 s19, s62, 3
	s_sub_i32 s7, s18, s19
	s_branch .LBB0_653
.Lup_b2:
	s_mul_hi_u32 s19, s18, 0xaaaaaaab
	s_lshr_b32 s62, s19, 1
	s_mul_i32 s19, s62, 3
	s_sub_i32 s7, s18, s19
	s_add_i32 s7, s7, 3
	s_branch .LBB0_653
.Lup_c:
	s_sub_i32 s18, s6, 0xa0
	s_lshl_b32 s18, s18, 2
	s_add_i32 s18, s18, s77
	s_addk_i32 s18, 0x30
	s_mul_hi_u32 s19, s18, 0xaaaaaaab
	s_lshr_b32 s62, s19, 1
	s_mul_i32 s19, s62, 3
	s_sub_i32 s7, s18, s19
	s_add_i32 s7, s7, 3
